# P3 loop mask block: redundant s_and chain removed and block moved out of line (fall-through steady state)
# speedup vs baseline: 1.0142x; 1.0142x over previous
.LBB0_325:
	s_waitcnt lgkmcnt(0)
	v_mfma_f32_32x32x16_bf16 v[96:111], v[80:83], v[144:147], v[64:79]
	v_mfma_f32_32x32x16_bf16 v[96:111], v[202:205], v[140:143], v[96:111]
	v_cvt_f32_i32_e32 v156, s100
	v_mfma_f32_32x32x16_bf16 v[96:111], v[194:197], v[136:139], v[96:111]
	v_fma_f32 v254, v208, v156, -v207
	v_mfma_f32_32x32x16_bf16 v[96:111], v[186:189], v[132:135], v[96:111]
	v_add_f32_e32 v255, v237, v254
	s_add_i32 s3, s79, 0xfffe8000
	s_and_b32 s3, s3, 0x18000
	v_add_u32_e32 v158, s3, v235
	v_add_u32_e32 v159, s3, v239
	v_add_u32_e32 v160, s3, v236
	v_add_u32_e32 v161, s3, v234
	ds_read_b64_tr_b16 v[182:183], v158 offset:32768
	ds_read_b64_tr_b16 v[184:185], v158 offset:34816
	ds_read_b64_tr_b16 v[178:179], v159 offset:32768
	ds_read_b64_tr_b16 v[180:181], v159 offset:34816
	ds_read_b64_tr_b16 v[148:149], v160 offset:32768
	ds_read_b64_tr_b16 v[150:151], v160 offset:34816
	ds_read_b64_tr_b16 v[152:153], v161 offset:32768
	ds_read_b64_tr_b16 v[154:155], v161 offset:34816
	v_mfma_f32_32x32x16_bf16 v[80:95], v[198:201], v[144:147], v[64:79]
	v_add_f32_e32 v96, v254, v96
	v_exp_f32_e32 v96, v96
	v_add_f32_e32 v97, v254, v97
	v_exp_f32_e32 v97, v97
	v_add_f32_e32 v98, v254, v98
	v_exp_f32_e32 v98, v98
	v_add_f32_e32 v99, v254, v99
	v_exp_f32_e32 v99, v99
	v_mfma_f32_32x32x16_bf16 v[80:95], v[190:193], v[140:143], v[80:95]
	v_add_f32_e32 v100, v254, v100
	v_exp_f32_e32 v100, v100
	v_add_f32_e32 v101, v254, v101
	v_exp_f32_e32 v101, v101
	v_add_f32_e32 v102, v254, v102
	v_exp_f32_e32 v102, v102
	v_add_f32_e32 v103, v254, v103
	v_exp_f32_e32 v103, v103
	v_mfma_f32_32x32x16_bf16 v[80:95], v[246:249], v[136:139], v[80:95]
	v_add_f32_e32 v104, v254, v104
	v_exp_f32_e32 v104, v104
	v_add_f32_e32 v105, v254, v105
	v_exp_f32_e32 v105, v105
	v_add_f32_e32 v106, v254, v106
	v_exp_f32_e32 v106, v106
	v_add_f32_e32 v107, v254, v107
	v_exp_f32_e32 v107, v107
	v_mfma_f32_32x32x16_bf16 v[80:95], v[250:253], v[132:135], v[80:95]
	v_add_f32_e32 v108, v254, v108
	v_exp_f32_e32 v108, v108
	v_add_f32_e32 v109, v254, v109
	v_exp_f32_e32 v109, v109
	v_add_f32_e32 v110, v254, v110
	v_exp_f32_e32 v110, v110
	v_add_f32_e32 v111, v254, v111
	v_exp_f32_e32 v111, v111
	s_cmp_le_i32 s72, s101
	s_cbranch_scc0 .Lmask_blk

.Lmask_blk:
	s_lshl_b32 s4, s72, 6
	v_subrev_u32_e32 v156, s4, v240
	v_cmp_gt_i32_e64 s[60:61], 26, v156
	v_cmp_gt_i32_e64 s[62:63], 27, v156
	v_cmp_gt_i32_e64 s[58:59], 25, v156
	v_cmp_gt_i32_e64 s[56:57], 24, v156
	v_cmp_gt_i32_e64 s[54:55], 19, v156
	v_cmp_gt_i32_e64 s[52:53], 18, v156
	v_cmp_gt_i32_e64 s[50:51], 17, v156
	v_cmp_gt_i32_e64 s[48:49], 16, v156
	v_cmp_gt_i32_e64 s[46:47], 11, v156
	v_cmp_gt_i32_e64 s[44:45], 10, v156
	v_cmp_gt_i32_e64 s[42:43], 9, v156
	v_cmp_gt_i32_e64 s[40:41], 8, v156
	v_cmp_gt_i32_e64 s[38:39], 3, v156
	v_cmp_gt_i32_e64 s[36:37], 2, v156
	v_cmp_gt_i32_e64 s[34:35], 1, v156
	v_cmp_gt_i32_e64 s[30:31], 0, v156
	v_cmp_gt_i32_e64 s[28:29], 58, v156
	s_nop 0
	v_cndmask_b32_e64 v96, v96, v113, s[30:31]
	v_cmp_gt_i32_e64 s[30:31], 59, v156
	v_cmp_gt_i32_e64 s[26:27], 57, v156
	v_cmp_gt_i32_e64 s[24:25], 56, v156
	v_cmp_gt_i32_e64 s[22:23], 51, v156
	v_cmp_gt_i32_e64 s[20:21], 50, v156
	v_cmp_gt_i32_e64 s[18:19], 49, v156
	v_cmp_gt_i32_e64 s[16:17], 48, v156
	v_cmp_gt_i32_e64 s[14:15], 43, v156
	v_cmp_gt_i32_e64 s[12:13], 42, v156
	v_cmp_gt_i32_e64 s[10:11], 41, v156
	v_cmp_gt_i32_e64 s[8:9], 40, v156
	v_cmp_gt_i32_e64 s[6:7], 35, v156
	v_cmp_gt_i32_e64 s[4:5], 34, v156
	v_cmp_gt_i32_e64 s[0:1], 33, v156
	v_cmp_gt_i32_e32 vcc, 32, v156
	v_cndmask_b32_e64 v111, v111, v113, s[62:63]
	v_cndmask_b32_e64 v110, v110, v113, s[60:61]
	v_cndmask_b32_e64 v109, v109, v113, s[58:59]
	v_cndmask_b32_e64 v108, v108, v113, s[56:57]
	v_cndmask_b32_e64 v107, v107, v113, s[54:55]
	v_cndmask_b32_e64 v106, v106, v113, s[52:53]
	v_cndmask_b32_e64 v105, v105, v113, s[50:51]
	v_cndmask_b32_e64 v104, v104, v113, s[48:49]
	v_cndmask_b32_e64 v103, v103, v113, s[46:47]
	v_cndmask_b32_e64 v102, v102, v113, s[44:45]
	v_cndmask_b32_e64 v101, v101, v113, s[42:43]
	v_cndmask_b32_e64 v100, v100, v113, s[40:41]
	v_cndmask_b32_e64 v99, v99, v113, s[38:39]
	v_cndmask_b32_e64 v98, v98, v113, s[36:37]
	v_cndmask_b32_e64 v97, v97, v113, s[34:35]
	v_cndmask_b32_e64 v95, v95, v228, s[30:31]
	v_cndmask_b32_e64 v94, v94, v228, s[28:29]
	v_cndmask_b32_e64 v93, v93, v228, s[26:27]
	v_cndmask_b32_e64 v92, v92, v228, s[24:25]
	v_cndmask_b32_e64 v91, v91, v228, s[22:23]
	v_cndmask_b32_e64 v90, v90, v228, s[20:21]
	v_cndmask_b32_e64 v89, v89, v228, s[18:19]
	v_cndmask_b32_e64 v88, v88, v228, s[16:17]
	v_cndmask_b32_e64 v87, v87, v228, s[14:15]
	v_cndmask_b32_e64 v86, v86, v228, s[12:13]
	v_cndmask_b32_e64 v85, v85, v228, s[10:11]
	v_cndmask_b32_e64 v84, v84, v228, s[8:9]
	v_cndmask_b32_e64 v83, v83, v228, s[6:7]
	v_cndmask_b32_e64 v82, v82, v228, s[4:5]
	v_cndmask_b32_e64 v81, v81, v228, s[0:1]
	v_cndmask_b32_e32 v80, v80, v228, vcc
	s_branch .LBB0_327
